# attention output store tail: v_permlane32_swap pairs so each lane stores 16 contiguous bytes (4 dwordx4 instead of 8 dwordx2)
# speedup vs baseline: 1.0022x; 1.0006x over previous
; DI unsigned pk2(float a, float b) { f32x2 v = {a, b}; bf2_t r = __builtin_convertvector(v, bf2_t); return __builtin_bit_cast(unsigned, r); }
; DI void attn_unit(const Params& p, int l, int b, int qtp, int grp, char* smem) {
;     ...
;   const int gcol = (grp == 2 ? 0 : grp == 1 ? 256 : grp == 0 ? 512 : 768) + w * 64 + 4 * h;
;   bf16_t* mrow = (bf16_t*)(p.ws + OFF_MIX) + (tok0 + qpos) * DM + gcol;
; #pragma unroll
;   for (int g = 0; g < 4; ++g) {
;     u32x2 a = {pk2(o0[4 * g], o0[4 * g + 1]), pk2(o0[4 * g + 2], o0[4 * g + 3])};
;     u32x2 c = {pk2(o1[4 * g], o1[4 * g + 1]), pk2(o1[4 * g + 2], o1[4 * g + 3])};
;     *(u32x2*)(mrow + 8 * g) = a;
;     *(u32x2*)(mrow + 32 + 8 * g) = c;
;   }
;   __syncthreads();
.LBB0_110:
	v_readlane_b32 s1, v244, 21
	s_cmp_lg_u32 s1, 1
	s_cselect_b32 s2, s0, 0x100
	v_readlane_b32 s0, v244, 9
	v_readlane_b32 s1, v244, 10
	s_and_b64 s[0:1], s[0:1], exec
	s_cselect_b32 s0, 0, s2
	v_or3_b32 v0, v159, v220, s0
	v_readlane_b32 s0, v246, 16
	v_lshlrev_b64 v[34:35], 11, v[156:157]
	v_readlane_b32 s1, v246, 17
	s_waitcnt vmcnt(0)
	v_lshl_add_u64 v[34:35], s[0:1], 0, v[34:35]
	v_lshl_add_u64 v[34:35], v[0:1], 1, v[34:35]
	v_cvt_pk_bf16_f32 v36, v18, v19
	v_cvt_pk_bf16_f32 v37, v20, v21
	v_cvt_pk_bf16_f32 v38, v22, v23
	v_cvt_pk_bf16_f32 v39, v24, v25
	v_cvt_pk_bf16_f32 v40, v26, v27
	v_cvt_pk_bf16_f32 v41, v28, v29
	v_cvt_pk_bf16_f32 v42, v30, v31
	v_cvt_pk_bf16_f32 v43, v32, v33
	v_cvt_pk_bf16_f32 v44, v2, v3
	v_cvt_pk_bf16_f32 v45, v4, v5
	v_cvt_pk_bf16_f32 v46, v6, v7
	v_cvt_pk_bf16_f32 v47, v8, v9
	v_cvt_pk_bf16_f32 v48, v10, v11
	v_cvt_pk_bf16_f32 v49, v12, v13
	v_cvt_pk_bf16_f32 v50, v14, v15
	v_cvt_pk_bf16_f32 v51, v16, v17
	v_and_b32_e32 v52, 32, v203
	v_lshrrev_b32_e32 v52, 2, v52
	v_mov_b32_e32 v53, 0
	v_lshl_add_u64 v[34:35], v[34:35], 0, v[52:53]
	v_permlane32_swap_b32_e32 v36, v38
	v_permlane32_swap_b32_e32 v37, v39
	v_permlane32_swap_b32_e32 v40, v42
	v_permlane32_swap_b32_e32 v41, v43
	v_permlane32_swap_b32_e32 v44, v46
	v_permlane32_swap_b32_e32 v45, v47
	v_permlane32_swap_b32_e32 v48, v50
	v_permlane32_swap_b32_e32 v49, v51
	global_store_dwordx4 v[34:35], v[36:39], off
	global_store_dwordx4 v[34:35], v[40:43], off offset:32
	global_store_dwordx4 v[34:35], v[44:47], off offset:64
	global_store_dwordx4 v[34:35], v[48:51], off offset:96
	s_barrier
